# speedup vs baseline: 1.0280x; 1.0025x over previous
; __device__ __forceinline__ void modulate_phase(const Params& p, int layer, int which, bool lat_only, bool from_input) {
;     ...
;     float4 v[4];
;     float ss = 0.f;
; #pragma unroll
;     for (int i = 0; i < 4; ++i) {
;       v[i] = *(const float4*)(xr + i * 256 + lane * 4);
;       ss += v[i].x * v[i].x + v[i].y * v[i].y + v[i].z * v[i].z + v[i].w * v[i].w;
;     }
;     ss = wave_sum(ss);
;     float r = rsqrtf(ss * (1.f / 1024.f) + 1e-6f);
; #pragma unroll
;     for (int i = 0; i < 4; ++i) {
;       int col = i * 256 + lane * 4;
;       float4 s4 = *(const float4*)(sh + col), c4 = *(const float4*)(sc + col);
;       uint2 o;
;       o.x = pack2(v[i].x * r * (1.f + c4.x) + s4.x, v[i].y * r * (1.f + c4.y) + s4.y);
;       o.y = pack2(v[i].z * r * (1.f + c4.z) + s4.z, v[i].w * r * (1.f + c4.w) + s4.w);
;       *(uint2*)(act + (size_t)row * D + col) = o;
;     }
.LBB0_419:
	s_or_b64 exec, exec, s[14:15]
	v_ashrrev_i32_e32 v1, 31, v0
	v_lshlrev_b64 v[0:1], v6, v[0:1]
	v_lshl_add_u64 v[0:1], v[4:5], 0, v[0:1]
	v_lshlrev_b64 v[2:3], 12, v[2:3]
	v_lshl_add_u64 v[0:1], v[0:1], 0, v[2:3]
	v_lshl_add_u64 v[0:1], v[0:1], 0, v[108:109]
	flat_load_dwordx4 v[22:25], v[0:1]
	flat_load_dwordx4 v[8:11], v[0:1] offset:1024
	flat_load_dwordx4 v[4:7], v[0:1] offset:2048
	s_nop 0
	flat_load_dwordx4 v[0:3], v[0:1] offset:3072
	v_add_u32_e32 v13, s81, v13
	v_mul_lo_u32 v26, v13, 6
	v_ashrrev_i32_e32 v27, 31, v26
	v_lshlrev_b64 v[26:27], 12, v[26:27]
	v_lshl_add_u64 v[30:31], s[8:9], 0, v[26:27]
	s_mov_b64 s[14:15], 0x4000
	v_lshl_add_u64 v[34:35], v[30:31], 0, s[14:15]
	v_lshl_add_u64 v[36:37], v[30:31], 0, v[108:109]
	s_movk_i32 s2, 0x3000
	v_lshl_add_u64 v[26:27], v[34:35], 0, v[108:109]
	v_add_co_u32_e32 v30, vcc, s2, v36
	flat_load_dwordx4 v[26:29], v[26:27]
	s_nop 0
	v_addc_co_u32_e32 v31, vcc, 0, v37, vcc
	flat_load_dwordx4 v[30:33], v[30:31]
	v_mov_b32_e32 v84, v16
	v_mov_b32_e32 v85, v109
	v_lshl_add_u64 v[84:85], v[34:35], 0, v[84:85]
	flat_load_dwordx4 v[60:63], v[84:85]
	v_mov_b32_e32 v84, v18
	v_mov_b32_e32 v85, v109
	v_lshl_add_u64 v[84:85], v[34:35], 0, v[84:85]
	flat_load_dwordx4 v[68:71], v[84:85]
	v_mov_b32_e32 v84, v20
	v_mov_b32_e32 v85, v109
	v_lshl_add_u64 v[84:85], v[34:35], 0, v[84:85]
	flat_load_dwordx4 v[76:79], v[84:85]
	s_mov_b64 s[14:15], 0x3000
	v_lshl_add_u64 v[86:87], v[36:37], 0, s[14:15]
	flat_load_dwordx4 v[64:67], v[86:87] offset:1024
	flat_load_dwordx4 v[72:75], v[86:87] offset:2048
	flat_load_dwordx4 v[80:83], v[86:87] offset:3072
	v_and_b32_e32 v17, 64, v213
	v_xor_b32_e32 v13, 16, v213
	v_add_u32_e32 v17, 64, v17
	v_cmp_lt_i32_e32 vcc, v13, v17
	v_xor_b32_e32 v21, 32, v213
	s_mov_b64 s[14:15], 0x3000
	v_cndmask_b32_e32 v13, v213, v13, vcc
	v_lshlrev_b32_e32 v13, 2, v13
	v_cmp_lt_i32_e32 vcc, v21, v17
	s_waitcnt vmcnt(0) lgkmcnt(0)
	v_mov_b32_e32 v44, v23
	v_mov_b32_e32 v45, v9
	v_mov_b32_e32 v42, v22
	v_mov_b32_e32 v43, v8
	v_mov_b32_e32 v52, v5
	v_mov_b32_e32 v53, v1
	v_pk_mul_f32 v[44:45], v[44:45], v[44:45]
	v_mov_b32_e32 v38, v24
	v_mov_b32_e32 v39, v10
	v_mov_b32_e32 v50, v4
	v_mov_b32_e32 v51, v0
	v_pk_mul_f32 v[52:53], v[52:53], v[52:53]
	v_pk_fma_f32 v[42:43], v[42:43], v[42:43], v[44:45]
	v_mov_b32_e32 v40, v25
	v_mov_b32_e32 v41, v11
	v_mov_b32_e32 v46, v6
	v_mov_b32_e32 v47, v2
	v_pk_fma_f32 v[44:45], v[50:51], v[50:51], v[52:53]
	v_pk_fma_f32 v[38:39], v[38:39], v[38:39], v[42:43]
	v_mov_b32_e32 v48, v7
	v_mov_b32_e32 v49, v3
	v_pk_fma_f32 v[42:43], v[46:47], v[46:47], v[44:45]
	v_pk_fma_f32 v[38:39], v[40:41], v[40:41], v[38:39]
	v_pk_fma_f32 v[40:41], v[48:49], v[48:49], v[42:43]
	v_add_f32_e32 v19, v38, v39
	v_add_f32_e32 v19, v19, v40
	v_add_f32_e32 v19, v19, v41
	v_cndmask_b32_e32 v17, v213, v21, vcc
	v_lshlrev_b32_e32 v17, 2, v17
	v_add_f32_dpp v19, v19, v19 row_ror:8 row_mask:0xf bank_mask:0xf bound_ctrl:1
	v_pk_add_f32 v[26:27], v[26:27], 1.0 op_sel_hi:[1,0]
	v_pk_add_f32 v[28:29], v[28:29], 1.0 op_sel_hi:[1,0]
	v_add_f32_dpp v19, v19, v19 row_ror:4 row_mask:0xf bank_mask:0xf bound_ctrl:1
	s_nop 1
	v_add_f32_dpp v19, v19, v19 row_ror:2 row_mask:0xf bank_mask:0xf bound_ctrl:1
	s_nop 1
	v_add_f32_dpp v19, v19, v19 row_ror:1 row_mask:0xf bank_mask:0xf bound_ctrl:1
	ds_bpermute_b32 v13, v13, v19
	s_waitcnt lgkmcnt(0)
	v_add_f32_e32 v19, v19, v13
	ds_bpermute_b32 v21, v17, v19
	v_ashrrev_i32_e32 v13, 31, v12
	v_lshlrev_b64 v[38:39], 11, v[12:13]
	v_mov_b32_e32 v17, v109
	v_lshl_add_u64 v[40:41], v[34:35], 0, v[16:17]
	s_waitcnt lgkmcnt(0)
	v_add_f32_e32 v13, v19, v21
	v_fmamk_f32 v13, v13, 0x3a800000, v205
	v_mul_f32_e32 v19, 0x4b800000, v13
	v_cmp_gt_f32_e32 vcc, s39, v13
	v_lshl_add_u64 v[38:39], v[14:15], 0, v[38:39]
	v_mov_b32_e32 v21, v109
	v_cndmask_b32_e32 v13, v13, v19, vcc
	v_rsq_f32_e32 v13, v13
	v_mov_b32_e32 v19, v109
	v_mul_f32_e32 v17, 0x45800000, v13
	v_cndmask_b32_e32 v42, v13, v17, vcc
	v_pk_mul_f32 v[22:23], v[22:23], v[42:43] op_sel_hi:[1,0]
	v_pk_mul_f32 v[24:25], v[24:25], v[42:43] op_sel_hi:[1,0]
	v_pk_fma_f32 v[22:23], v[26:27], v[22:23], v[30:31]
	v_pk_fma_f32 v[24:25], v[28:29], v[24:25], v[32:33]
	v_cvt_pk_bf16_f32 v22, v22, v23
	v_cvt_pk_bf16_f32 v23, v24, v25
	flat_store_dwordx2 v[38:39], v[22:23]
	v_pk_mul_f32 v[8:9], v[8:9], v[42:43] op_sel_hi:[1,0]
	v_pk_mul_f32 v[10:11], v[10:11], v[42:43] op_sel_hi:[1,0]
	v_lshl_add_u64 v[32:33], v[34:35], 0, v[18:19]
	v_pk_mul_f32 v[4:5], v[4:5], v[42:43] op_sel_hi:[1,0]
	v_pk_mul_f32 v[6:7], v[6:7], v[42:43] op_sel_hi:[1,0]
	v_pk_mul_f32 v[0:1], v[0:1], v[42:43] op_sel_hi:[1,0]
	v_pk_mul_f32 v[2:3], v[2:3], v[42:43] op_sel_hi:[1,0]
	v_pk_add_f32 v[60:61], v[60:61], 1.0 op_sel_hi:[1,0]
	v_pk_add_f32 v[62:63], v[62:63], 1.0 op_sel_hi:[1,0]
	v_pk_fma_f32 v[8:9], v[8:9], v[60:61], v[64:65]
	v_pk_fma_f32 v[10:11], v[10:11], v[62:63], v[66:67]
	v_cvt_pk_bf16_f32 v8, v8, v9
	v_cvt_pk_bf16_f32 v9, v10, v11
	flat_store_dwordx2 v[38:39], v[8:9] offset:512
	v_lshl_add_u64 v[26:27], v[34:35], 0, v[20:21]
	v_pk_add_f32 v[68:69], v[68:69], 1.0 op_sel_hi:[1,0]
	v_pk_add_f32 v[70:71], v[70:71], 1.0 op_sel_hi:[1,0]
	v_pk_fma_f32 v[4:5], v[4:5], v[68:69], v[72:73]
	v_pk_fma_f32 v[6:7], v[6:7], v[70:71], v[74:75]
	v_cvt_pk_bf16_f32 v4, v4, v5
	v_cvt_pk_bf16_f32 v5, v6, v7
	flat_store_dwordx2 v[38:39], v[4:5] offset:1024
	v_pk_add_f32 v[76:77], v[76:77], 1.0 op_sel_hi:[1,0]
	v_pk_add_f32 v[78:79], v[78:79], 1.0 op_sel_hi:[1,0]
	v_pk_fma_f32 v[0:1], v[0:1], v[76:77], v[80:81]
	v_pk_fma_f32 v[2:3], v[2:3], v[78:79], v[82:83]
	v_cvt_pk_bf16_f32 v0, v0, v1
	v_cvt_pk_bf16_f32 v1, v2, v3
	flat_store_dwordx2 v[38:39], v[0:1] offset:1536
